# attention tile: removed the identity parts (denormal scaling, infinity select, zero offset) of the accurate-log expansion for log(1+exp(-|z|))
# speedup vs baseline: 1.0090x; 1.0034x over previous
; __device__ __forceinline__ void attn_tile(const Ctx& F, int bh, int qt, int kt, const bf16x8 (&qf)[4], f32x16& o0, f32x16& o1, float& carry) {
;     ...
;     for (int r = 0; r < 16; ++r) {
;         const float z = sT[r] * 0.125f;
;         const float sp = fmaxf(z, 0.f) + __logf(1.f + __expf(-fabsf(z)));
;         const int key = s0 + (r & 3) + 8 * (r >> 2) + 4 * hi;
;         const bool valid = !diag || (key < qpos);
;         lk[r] = valid ? -sp : 0.f;
;         lz[r] = valid ? (z - sp) : -1e30f;
;     }
.Lkpf_join:
	s_nop 11
	v_mul_f32_e32 v2, 0x3e000000, v82
	v_mul_f32_e32 v16, 0x3e000000, v83
	v_max_f32_e32 v197, 0, v2
	v_mul_f32_e64 v2, |v2|, s79
	v_mul_f32_e32 v149, 0x3e000000, v84
	v_max_f32_e32 v216, 0, v16
	v_mul_f32_e64 v16, |v16|, s79
	v_exp_f32_e32 v2, v2
	v_mul_f32_e32 v193, 0x3e000000, v85
	v_max_f32_e32 v217, 0, v149
	v_mul_f32_e64 v149, |v149|, s79
	v_exp_f32_e32 v16, v16
	v_mul_f32_e32 v195, 0x3e000000, v86
	v_max_f32_e32 v218, 0, v193
	v_mul_f32_e64 v193, |v193|, s79
	v_exp_f32_e32 v149, v149
	v_max_f32_e32 v219, 0, v195
	v_mul_f32_e64 v195, |v195|, s79
	v_exp_f32_e32 v193, v193
	v_mul_f32_e32 v196, 0x3e000000, v87
	v_exp_f32_e32 v195, v195
	v_add_f32_e32 v2, 1.0, v2
	v_mul_f32_e64 v215, |v196|, s79
	v_add_f32_e32 v16, 1.0, v16
	v_exp_f32_e32 v220, v215
	v_add_f32_e32 v149, 1.0, v149
	v_add_f32_e32 v193, 1.0, v193
	v_add_f32_e32 v195, 1.0, v195
	v_log_f32_e32 v2, v2
	v_log_f32_e32 v16, v16
	v_log_f32_e32 v149, v149
	v_log_f32_e32 v193, v193
	v_log_f32_e32 v195, v195
	v_mul_f32_e32 v225, 0x3f317217, v2
	v_mul_f32_e32 v226, 0x3f317217, v16
	v_fma_f32 v225, v2, s57, -v225
	v_mul_f32_e32 v227, 0x3f317217, v149
	v_fma_f32 v226, v16, s57, -v226
	v_fmac_f32_e32 v225, 0x3377d1cf, v2
	v_mul_f32_e32 v228, 0x3f317217, v193
	v_fma_f32 v227, v149, s57, -v227
	v_fmac_f32_e32 v226, 0x3377d1cf, v16
	v_fmac_f32_e32 v225, 0x3f317217, v2
	v_mul_f32_e32 v229, 0x3f317217, v195
	v_fma_f32 v228, v193, s57, -v228
	v_fmac_f32_e32 v227, 0x3377d1cf, v149
	v_fmac_f32_e32 v226, 0x3f317217, v16
	v_mov_b32_e32 v2, v225
	v_fma_f32 v229, v195, s57, -v229
	v_fmac_f32_e32 v228, 0x3377d1cf, v193
	v_fmac_f32_e32 v227, 0x3f317217, v149
	v_mov_b32_e32 v16, v226
	v_fmac_f32_e32 v229, 0x3377d1cf, v195
	v_fmac_f32_e32 v228, 0x3f317217, v193
	v_mov_b32_e32 v149, v227
	v_fmac_f32_e32 v229, 0x3f317217, v195
	v_mov_b32_e32 v193, v228
	v_mov_b32_e32 v195, v229
	v_mov_b32_e32 v222, v195
	v_add_f32_e32 v195, v216, v16
	v_add_f32_e32 v16, 1.0, v220
	s_or_b64 s[26:27], vcc, s[90:91]
	s_or_b64 vcc, s[28:29], s[90:91]
	v_cmp_lt_u32_e64 s[28:29], v148, v146
	v_log_f32_e32 v16, v16
	v_add_f32_e32 v215, v197, v2
	s_or_b64 s[24:25], s[22:23], s[90:91]
	v_mul_f32_e32 v197, 0x3f317217, v16
	v_fma_f32 v197, v16, s57, -v197
	v_fmac_f32_e32 v197, 0x3377d1cf, v16
	s_or_b64 s[22:23], s[30:31], s[90:91]
	v_fmac_f32_e32 v197, 0x3f317217, v16
	v_max_f32_e32 v196, 0, v196
	v_add_f32_e32 v219, v219, v222
	v_mov_b32_e32 v16, v197
	v_mul_f32_e32 v197, 0x3e000000, v88
	v_mul_f32_e64 v220, |v197|, s79
	v_exp_f32_e32 v220, v220
	v_add_f32_e32 v222, v196, v16
	v_or_b32_e32 v16, 9, v17
	v_cmp_lt_u32_e64 s[0:1], v16, v146
	v_add_f32_e32 v16, 1.0, v220
	s_or_b64 s[30:31], s[0:1], s[90:91]
	v_mov_b32_e32 v221, v193
	v_log_f32_e32 v196, v16
	v_add_f32_e32 v2, v218, v221
	v_max_f32_e32 v197, 0, v197
	v_add_f32_e32 v193, v217, v149
	v_mul_f32_e32 v220, 0x3f317217, v196
	v_fma_f32 v220, v196, s57, -v220
	v_fmac_f32_e32 v220, 0x3377d1cf, v196
	v_fmac_f32_e32 v220, 0x3f317217, v196
	v_cndmask_b32_e64 v149, 0, -v215, s[26:27]
	v_cndmask_b32_e64 v216, 0, -v195, s[24:25]
	v_mov_b32_e32 v196, v220
	v_mul_f32_e32 v220, 0x3e000000, v89
	v_mul_f32_e64 v221, |v220|, s79
	v_exp_f32_e32 v221, v221
	v_add_f32_e32 v223, v197, v196
	v_or_b32_e32 v196, 10, v17
	v_cmp_lt_u32_e64 s[0:1], v196, v146
	v_add_f32_e32 v196, 1.0, v221
	s_or_b64 s[34:35], s[0:1], s[90:91]
	v_max_f32_e32 v220, 0, v220
	v_log_f32_e32 v197, v196
	v_cndmask_b32_e64 v217, 0, -v193, s[22:23]
	v_cndmask_b32_e64 v218, 0, -v2, vcc
	v_mul_f32_e32 v221, 0x3f317217, v197
	v_fma_f32 v221, v197, s57, -v221
	v_fmac_f32_e32 v221, 0x3377d1cf, v197
	v_fmac_f32_e32 v221, 0x3f317217, v197
	s_or_b64 s[28:29], s[28:29], s[90:91]
	v_cndmask_b32_e64 v148, 0, -v219, s[28:29]
	v_mov_b32_e32 v197, v221
	v_mul_f32_e32 v221, 0x3e000000, v90
	v_mul_f32_e64 v224, |v221|, s79
	v_exp_f32_e32 v224, v224
	v_add_f32_e32 v225, v220, v197
	v_cndmask_b32_e64 v16, 0, -v222, s[30:31]
	v_add_f32_e32 v197, 1.0, v224
	v_cndmask_b32_e64 v196, 0, -v223, s[34:35]
	v_fma_f32 v86, v86, s78, -v219
	v_log_f32_e32 v197, v197
	v_or_b32_e32 v220, 11, v17
	v_cmp_lt_u32_e64 s[36:37], v220, v146
	v_max_f32_e32 v220, 0, v221
	v_mul_f32_e32 v221, 0x3f317217, v197
	v_fma_f32 v221, v197, s57, -v221
	v_fmac_f32_e32 v221, 0x3377d1cf, v197
	v_fmac_f32_e32 v221, 0x3f317217, v197
	v_cndmask_b32_e64 v86, v214, v86, s[28:29]
	v_fma_f32 v82, v82, s78, -v215
	v_mov_b32_e32 v197, v221
	v_mul_f32_e32 v221, 0x3e000000, v91
	v_mul_f32_e64 v224, |v221|, s79
	v_exp_f32_e32 v224, v224
	v_add_f32_e32 v226, v220, v197
	v_or_b32_e32 v197, 16, v17
	v_cmp_lt_u32_e64 s[0:1], v197, v146
	v_add_f32_e32 v197, 1.0, v224
	s_or_b64 s[38:39], s[0:1], s[90:91]
	v_max_f32_e32 v221, 0, v221
	v_log_f32_e32 v197, v197
	v_cndmask_b32_e64 v220, 0, -v226, s[38:39]
	v_fma_f32 v90, v90, s78, -v226
	v_cndmask_b32_e64 v226, v214, v90, s[38:39]
	v_mul_f32_e32 v224, 0x3f317217, v197
	v_fma_f32 v224, v197, s57, -v224
	v_fmac_f32_e32 v224, 0x3377d1cf, v197
	v_fmac_f32_e32 v224, 0x3f317217, v197
	v_fma_f32 v83, v83, s78, -v195
	v_fma_f32 v84, v84, s78, -v193
	v_mov_b32_e32 v197, v224
	v_mul_f32_e32 v224, 0x3e000000, v92
	v_mul_f32_e64 v227, |v224|, s79
	v_exp_f32_e32 v227, v227
	v_add_f32_e32 v228, v221, v197
	v_or_b32_e32 v197, 17, v17
	v_cmp_lt_u32_e64 s[0:1], v197, v146
	v_add_f32_e32 v197, 1.0, v227
	s_or_b64 s[42:43], s[0:1], s[90:91]
	v_cndmask_b32_e64 v227, 0, -v228, s[42:43]
	v_log_f32_e32 v197, v197
	v_max_f32_e32 v221, 0, v224
	v_fma_f32 v90, v91, s78, -v228
	v_cndmask_b32_e64 v228, v214, v90, s[42:43]
	v_mul_f32_e32 v224, 0x3f317217, v197
	v_fma_f32 v224, v197, s57, -v224
	v_fmac_f32_e32 v224, 0x3377d1cf, v197
	v_fmac_f32_e32 v224, 0x3f317217, v197
; __device__ __forceinline__ void attn_tile(const Ctx& F, int bh, int qt, int kt, const bf16x8 (&qf)[4], f32x16& o0, f32x16& o1, float& carry) {
;     ...
;     for (int r = 0; r < 16; ++r) {
;         const float z = sT[r] * 0.125f;
;         const float sp = fmaxf(z, 0.f) + __logf(1.f + __expf(-fabsf(z)));
;         const int key = s0 + (r & 3) + 8 * (r >> 2) + 4 * hi;
;         const bool valid = !diag || (key < qpos);
;         lk[r] = valid ? -sp : 0.f;
;         lz[r] = valid ? (z - sp) : -1e30f;
;     }
;     float g[4], pg[4];
; #pragma unroll
;     for (int q = 0; q < 4; ++q) { g[q] = (lk[4 * q] + lk[4 * q + 1]) + (lk[4 * q + 2] + lk[4 * q + 3]); pg[q] = __shfl_xor(g[q], 32); }
	v_fma_f32 v2, v85, s78, -v2
	v_cndmask_b32_e64 v82, v214, v82, s[26:27]
	v_mov_b32_e32 v197, v224
	v_mul_f32_e32 v224, 0x3e000000, v93
	v_mul_f32_e64 v229, |v224|, s79
	v_exp_f32_e32 v229, v229
	v_add_f32_e32 v230, v221, v197
	v_or_b32_e32 v197, 18, v17
	v_cmp_lt_u32_e64 s[0:1], v197, v146
	v_add_f32_e32 v197, 1.0, v229
	s_or_b64 s[46:47], s[0:1], s[90:91]
	v_cndmask_b32_e64 v229, 0, -v230, s[46:47]
	v_log_f32_e32 v197, v197
	v_max_f32_e32 v221, 0, v224
	v_fma_f32 v90, v92, s78, -v230
	v_cndmask_b32_e64 v92, v214, v90, s[46:47]
	v_mul_f32_e32 v224, 0x3f317217, v197
	v_fma_f32 v224, v197, s57, -v224
	v_fmac_f32_e32 v224, 0x3377d1cf, v197
	v_fmac_f32_e32 v224, 0x3f317217, v197
	v_cndmask_b32_e64 v83, v214, v83, s[24:25]
	v_cndmask_b32_e64 v84, v214, v84, s[22:23]
	v_mov_b32_e32 v197, v224
	v_mul_f32_e32 v224, 0x3e000000, v94
	v_mul_f32_e64 v231, |v224|, s79
	v_exp_f32_e32 v231, v231
	v_add_f32_e32 v232, v221, v197
	v_or_b32_e32 v197, 19, v17
	v_cmp_lt_u32_e64 s[0:1], v197, v146
	v_add_f32_e32 v197, 1.0, v231
	s_or_b64 s[48:49], s[0:1], s[90:91]
	v_cndmask_b32_e64 v231, 0, -v232, s[48:49]
	v_log_f32_e32 v197, v197
	v_max_f32_e32 v221, 0, v224
	v_cndmask_b32_e32 v2, v214, v2, vcc
	v_mul_f32_e32 v224, 0x3f317217, v197
	v_fma_f32 v224, v197, s57, -v224
	v_fmac_f32_e32 v224, 0x3377d1cf, v197
	v_fmac_f32_e32 v224, 0x3f317217, v197
	s_nop 1
	v_mov_b32_e32 v197, v224
	v_mul_f32_e32 v224, 0x3e000000, v95
	v_mul_f32_e64 v233, |v224|, s79
	v_exp_f32_e32 v233, v233
	v_add_f32_e32 v234, v221, v197
	v_or_b32_e32 v197, 24, v17
	v_cmp_lt_u32_e64 s[0:1], v197, v146
	v_add_f32_e32 v197, 1.0, v233
	s_or_b64 s[40:41], s[0:1], s[90:91]
	v_cndmask_b32_e64 v233, 0, -v234, s[40:41]
	v_log_f32_e32 v197, v197
	v_max_f32_e32 v221, 0, v224
	v_mul_f32_e32 v224, 0x3f317217, v197
	v_fma_f32 v224, v197, s57, -v224
	v_fmac_f32_e32 v224, 0x3377d1cf, v197
	v_fmac_f32_e32 v224, 0x3f317217, v197
	s_nop 1
	v_mov_b32_e32 v197, v224
	v_mul_f32_e32 v224, 0x3e000000, v96
	v_mul_f32_e64 v235, |v224|, s79
	v_exp_f32_e32 v235, v235
	v_add_f32_e32 v236, v221, v197
	v_or_b32_e32 v197, 25, v17
	v_cmp_lt_u32_e64 s[0:1], v197, v146
	v_add_f32_e32 v197, 1.0, v235
	s_or_b64 s[44:45], s[0:1], s[90:91]
	v_cndmask_b32_e64 v235, 0, -v236, s[44:45]
	v_log_f32_e32 v197, v197
	v_max_f32_e32 v221, 0, v224
	v_mul_f32_e32 v224, 0x3f317217, v197
	v_fma_f32 v224, v197, s57, -v224
	v_fmac_f32_e32 v224, 0x3377d1cf, v197
	v_fmac_f32_e32 v224, 0x3f317217, v197
	s_nop 1
	v_mov_b32_e32 v197, v224
	v_mul_f32_e32 v224, 0x3e000000, v97
	v_mul_f32_e64 v237, |v224|, s79
	v_exp_f32_e32 v237, v237
	v_add_f32_e32 v238, v221, v197
	v_or_b32_e32 v197, 26, v17
	v_cmp_lt_u32_e64 s[0:1], v197, v146
	v_add_f32_e32 v197, 1.0, v237
	s_or_b64 s[50:51], s[0:1], s[90:91]
	v_or_b32_e32 v17, 27, v17
	v_log_f32_e32 v197, v197
	v_max_f32_e32 v221, 0, v224
	v_cndmask_b32_e64 v237, 0, -v238, s[50:51]
	v_mul_f32_e32 v224, 0x3f317217, v197
	v_fma_f32 v224, v197, s57, -v224
	v_fmac_f32_e32 v224, 0x3377d1cf, v197
	v_fmac_f32_e32 v224, 0x3f317217, v197
	s_nop 1
	v_mov_b32_e32 v197, v224
	v_cmp_lt_u32_e64 s[0:1], v17, v146
	v_and_b32_e32 v146, 64, v213
	v_xor_b32_e32 v17, 32, v213
	v_add_u32_e32 v146, 64, v146
	s_or_b64 s[52:53], s[0:1], s[90:91]
	v_cmp_lt_i32_e64 s[0:1], v17, v146
	v_add_f32_e32 v224, v221, v197
	s_nop 0
	v_cndmask_b32_e64 v17, v213, v17, s[0:1]
	v_lshlrev_b32_e32 v146, 2, v17
	v_add_f32_e32 v17, v149, v216
	v_add_f32_e32 v149, v217, v218
	v_cndmask_b32_e64 v239, 0, -v224, s[52:53]
	v_add_f32_e32 v240, v17, v149
	v_add_f32_e32 v17, v220, v227
	v_add_f32_e32 v149, v229, v231
	v_add_f32_e32 v197, v17, v149
	v_add_f32_e32 v17, v233, v235
	v_add_f32_e32 v149, v237, v239
	v_add_f32_e32 v149, v17, v149
	ds_bpermute_b32 v221, v146, v197
	ds_bpermute_b32 v17, v146, v149
	s_or_b64 s[0:1], s[36:37], s[90:91]
	v_cndmask_b32_e64 v220, 0, -v225, s[0:1]
	ds_bpermute_b32 v241, v146, v240
	s_waitcnt lgkmcnt(2)
	v_cndmask_b32_e64 v242, 0, v221, s[20:21]
	s_waitcnt lgkmcnt(1)
	v_pk_add_f32 v[90:91], v[148:149], v[16:17]
	v_pk_add_f32 v[148:149], v[196:197], v[220:221]
	v_cndmask_b32_e64 v243, 0, v17, s[20:21]
	v_pk_add_f32 v[148:149], v[90:91], v[148:149]
	ds_bpermute_b32 v17, v146, v148
	v_fma_f32 v90, v93, s78, -v232
	v_add_f32_e32 v91, v185, v91
	v_cndmask_b32_e64 v90, v214, v90, s[48:49]
	v_add_f32_e32 v91, v242, v91
	s_waitcnt lgkmcnt(0)
; __device__ __forceinline__ unsigned pk2(float lo, float hi) { f32x2 v = {lo, hi}; h16x2 b = __builtin_convertvector(v, h16x2); return __builtin_bit_cast(unsigned, b); }
; #define MFMA32(a, b, c) __builtin_amdgcn_mfma_f32_32x32x16_f16(H8(a), H8(b), (c), 0, 0, 0)
; __device__ __forceinline__ void attn_tile(const Ctx& F, int bh, int qt, int kt, const bf16x8 (&qf)[4], f32x16& o0, f32x16& o1, float& carry) {
;     ...
;     float g[4], pg[4];
; #pragma unroll
;     for (int q = 0; q < 4; ++q) { g[q] = (lk[4 * q] + lk[4 * q + 1]) + (lk[4 * q + 2] + lk[4 * q + 3]); pg[q] = __shfl_xor(g[q], 32); }
;     float Tq[4]; Tq[3] = 0.f; Tq[2] = g[3] + pg[3]; Tq[1] = Tq[2] + (g[2] + pg[2]); Tq[0] = Tq[1] + (g[1] + pg[1]);
;     const float total = Tq[0] + (g[0] + pg[0]);
;     float w[16];
; #pragma unroll
;     for (int q = 0; q < 4; ++q) {
;         const float after = carry + Tq[q] + (hi == 0 ? pg[q] : 0.f);
;         const float l3 = after, l2 = l3 + lk[4 * q + 3], l1 = l2 + lk[4 * q + 2], l0 = l1 + lk[4 * q + 1];
;         w[4 * q + 3] = __expf(lz[4 * q + 3] + l3); w[4 * q + 2] = __expf(lz[4 * q + 2] + l2);
;         w[4 * q + 1] = __expf(lz[4 * q + 1] + l1); w[4 * q + 0] = __expf(lz[4 * q + 0] + l0);
;     }
;     carry += total;
;     bf16x8 pw[2];
; #pragma unroll
;     for (int s = 0; s < 2; ++s) { u32x4 t; t.x = pk2(w[8 * s], w[8 * s + 1]); t.y = pk2(w[8 * s + 2], w[8 * s + 3]); t.z = pk2(w[8 * s + 4], w[8 * s + 5]); t.w = pk2(w[8 * s + 6], w[8 * s + 7]); pw[s] = __builtin_bit_cast(bf16x8, t); }
; #pragma unroll
;     for (int s = 0; s < 2; ++s) { o0 = MFMA32(vf[0][s], pw[s], o0); o1 = MFMA32(vf[1][s], pw[s], o1); }
; }
	v_cndmask_b32_e64 v93, 0, v17, s[20:21]
	v_add_f32_e32 v197, v231, v91
	v_add_f32_e32 v90, v90, v91
	v_add_f32_e32 v91, v185, v149
	v_add_f32_e32 v91, v93, v91
	v_add_f32_e32 v93, v220, v91
	v_add_f32_e32 v196, v196, v93
	v_add_f32_e32 v17, v148, v17
	v_add_f32_e32 v16, v16, v196
	v_add_f32_e32 v17, v17, v149
	v_cndmask_b32_e64 v233, 0, v241, s[20:21]
	v_add_f32_e32 v16, v86, v16
	v_fma_f32 v86, v87, s78, -v222
	v_fma_f32 v87, v88, s78, -v223
	v_fma_f32 v88, v89, s78, -v225
	v_add_f32_e32 v89, v185, v17
	v_cndmask_b32_e64 v88, v214, v88, s[0:1]
	v_add_f32_e32 v89, v233, v89
	v_cndmask_b32_e64 v87, v214, v87, s[34:35]
	v_add_f32_e32 v88, v88, v91
	v_add_f32_e32 v91, v218, v89
	v_add_f32_e32 v87, v87, v93
	v_add_f32_e32 v93, v217, v91
	v_cndmask_b32_e64 v86, v214, v86, s[30:31]
	v_add_f32_e32 v148, v216, v93
	v_add_f32_e32 v86, v86, v196
	v_add_f32_e32 v82, v82, v148
	v_add_f32_e32 v83, v83, v93
	v_add_f32_e32 v84, v84, v91
	v_add_f32_e32 v2, v2, v89
	v_mul_f32_e32 v16, 0x3fb8aa3b, v16
	v_mul_f32_e32 v86, 0x3fb8aa3b, v86
	v_mul_f32_e32 v87, 0x3fb8aa3b, v87
	v_mul_f32_e32 v88, 0x3fb8aa3b, v88
	v_mul_f32_e32 v82, 0x3fb8aa3b, v82
	v_mul_f32_e32 v83, 0x3fb8aa3b, v83
	v_mul_f32_e32 v84, 0x3fb8aa3b, v84
	v_mul_f32_e32 v2, 0x3fb8aa3b, v2
	v_exp_f32_e32 v16, v16
	v_exp_f32_e32 v86, v86
	v_exp_f32_e32 v87, v87
	v_exp_f32_e32 v88, v88
	v_exp_f32_e32 v82, v82
	v_exp_f32_e32 v83, v83
	v_exp_f32_e32 v84, v84
	v_exp_f32_e32 v2, v2
	v_fma_f32 v85, v97, s78, -v224
	v_cndmask_b32_e64 v85, v214, v85, s[52:53]
	v_fma_f32 v93, v94, s78, -v234
	v_add_f32_e32 v94, v244, v243
	v_fma_f32 v91, v95, s78, -v236
	v_add_f32_e32 v95, v239, v94
	v_add_f32_e32 v85, v94, v85
	v_add_f32_e32 v219, v229, v197
	v_fma_f32 v89, v96, s78, -v238
	v_add_f32_e32 v96, v237, v95
	v_mul_f32_e32 v94, 0x3fb8aa3b, v85
	v_cvt_pk_f16_f32 v82, v82, v83
	v_cvt_pk_f16_f32 v83, v84, v2
	v_cvt_pk_f16_f32 v84, v16, v86
	v_cvt_pk_f16_f32 v85, v87, v88
	v_add_f32_e32 v221, v227, v219
	v_cndmask_b32_e64 v89, v214, v89, s[50:51]
	v_cndmask_b32_e64 v91, v214, v91, s[44:45]
	v_cndmask_b32_e64 v93, v214, v93, s[40:41]
	v_add_f32_e32 v97, v235, v96
	s_waitcnt vmcnt(6)
	v_mfma_f32_32x32x16_f16 v[66:81], v[158:161], v[82:85], v[66:81]
	v_add_f32_e32 v221, v226, v221
	v_add_f32_e32 v219, v228, v219
	v_add_f32_e32 v92, v92, v197
	v_add_f32_e32 v16, v89, v95
	v_add_f32_e32 v86, v91, v96
	v_add_f32_e32 v87, v93, v97
	v_mul_f32_e32 v221, 0x3fb8aa3b, v221
	s_waitcnt vmcnt(2)
	v_mfma_f32_32x32x16_f16 v[50:65], v[12:15], v[82:85], v[50:65]
	v_mul_f32_e32 v219, 0x3fb8aa3b, v219
	v_mul_f32_e32 v92, 0x3fb8aa3b, v92
	v_mul_f32_e32 v90, 0x3fb8aa3b, v90
	v_mul_f32_e32 v16, 0x3fb8aa3b, v16
	v_mul_f32_e32 v86, 0x3fb8aa3b, v86
	v_mul_f32_e32 v12, 0x3fb8aa3b, v87
	v_exp_f32_e32 v221, v221
	v_exp_f32_e32 v219, v219
	v_exp_f32_e32 v92, v92
	v_exp_f32_e32 v90, v90
	v_exp_f32_e32 v2, v94
	v_exp_f32_e32 v86, v86
	v_exp_f32_e32 v14, v12
	v_exp_f32_e32 v15, v16
	v_cvt_pk_f16_f32 v12, v221, v219
	v_cvt_pk_f16_f32 v13, v92, v90
	v_cvt_pk_f16_f32 v14, v14, v86
	v_cvt_pk_f16_f32 v15, v15, v2
	v_add_f32_e32 v2, v240, v241
	s_cmp_eq_u32 s81, 0
	v_mfma_f32_32x32x16_f16 v[66:81], v[4:7], v[12:15], v[66:81]
	v_add_f32_e32 v2, v2, v17
	s_cselect_b64 s[0:1], -1, 0
	v_add_f32_e32 v185, v185, v2
	s_and_b64 vcc, exec, s[0:1]
	s_waitcnt vmcnt(0)
	v_mfma_f32_32x32x16_f16 v[50:65], v[8:11], v[12:15], v[50:65]
	s_cbranch_vccnz .LBB0_675
	s_add_i32 s81, s81, -1
	v_cmp_gt_f32_e32 vcc, s76, v185
	s_cmp_eq_u64 vcc, exec
	s_cselect_b64 s[0:1], -1, 0
	s_andn2_b64 vcc, exec, s[0:1]
	s_cbranch_vccz .LBB0_676
	s_ashr_i32 s0, s92, 7
	s_lshl_b32 s1, s0, 9
	s_and_b32 s1, s1, 0xfffff000
	s_lshl_b32 s100, s81, 5
	s_or_b32 s1, s1, s100
	s_lshl_b32 s0, s0, 6
	s_and_b32 s0, s0, 0x1c0
	v_or_b32_e32 v220, s1, v170
	v_lshlrev_b32_e32 v220, 10, v220
	v_or3_b32 v220, v220, v202, s0
	v_or_b32_e32 v220, 0x200, v220
	v_mov_b32_e32 v221, 0
	v_lshl_add_u64 v[220:221], v[220:221], 1, s[68:69]
	s_mov_b32 s99, 1
	s_branch .LBB0_677
